# in-proj epi_rownorm ladders (phase 3): 64 serialized LDS reads batched 10-13 in flight, fmac order unchanged
# speedup vs baseline: 1.0018x; 1.0018x over previous
; #define TIDX (tid_launder())
; DI void epi_rownorm(const float* Ct, float* rn, int W) {
;   const int row = TIDX >> 1, grp = TIDX & 1;
;   float ss = 0.f;
;   for (int c0 = 0; c0 < 64; ++c0) { const int c = (c0 + row) & 63; const float v = Ct[row * 132 + grp * 64 + c]; ss += v * v; }
;   if (W == 128) { ss += __shfl_xor(ss, 1); ss *= 0.5f; }
;   rn[row * 2 + grp] = rsqrtf(ss * (1.f / 64.f) + 1e-6f);
;   __syncthreads();
; }
.LBB0_1982:
	s_andn2_b64 vcc, exec, s[0:1]
	s_cbranch_vccnz .LBB0_2011
	v_mov_b32_e32 v0, v230
	v_mov_b32_e32 v2, v230
	s_mov_b32 s0, 0x800000
	v_ashrrev_i32_e32 v3, 1, v0
	v_and_b32_e32 v2, 1, v2
	v_mul_lo_u32 v4, v3, s79
	v_add_u32_e32 v7, 55, v3
	v_lshl_add_u32 v4, v2, 8, v4
	v_and_b32_e32 v5, 63, v3
	v_and_b32_e32 v7, 63, v7
	v_lshl_add_u32 v5, v5, 2, v4
	v_lshl_add_u32 v7, v7, 2, v4
	ds_read_b32 v6, v5
	ds_read_b32 v7, v7
	v_add_u32_e32 v5, 1, v3
	v_and_b32_e32 v5, 63, v5
	v_lshl_add_u32 v5, v5, 2, v4
	ds_read_b32 v5, v5
	v_mov_b32_e32 v18, v230
	s_mov_b64 s[6:7], -1
	v_mov_b32_e32 v11, 1.0
	v_mov_b32_e32 v10, 1.0
	s_waitcnt lgkmcnt(0)
	v_mul_f32_e32 v5, v5, v5
	v_fmac_f32_e32 v5, v6, v6
	v_add_u32_e32 v6, 2, v3
	v_and_b32_e32 v6, 63, v6
	v_lshl_add_u32 v6, v6, 2, v4
	ds_read_b32 v6, v6
	v_add_u32_e32 v9, 3, v3
	v_and_b32_e32 v9, 63, v9
	v_lshl_add_u32 v9, v9, 2, v4
	ds_read_b32 v9, v9
	v_add_u32_e32 v12, 4, v3
	v_and_b32_e32 v12, 63, v12
	v_lshl_add_u32 v12, v12, 2, v4
	ds_read_b32 v12, v12
	v_add_u32_e32 v13, 5, v3
	v_and_b32_e32 v13, 63, v13
	v_lshl_add_u32 v13, v13, 2, v4
	ds_read_b32 v13, v13
	v_add_u32_e32 v14, 6, v3
	v_and_b32_e32 v14, 63, v14
	v_lshl_add_u32 v14, v14, 2, v4
	ds_read_b32 v14, v14
	v_add_u32_e32 v15, 7, v3
	v_and_b32_e32 v15, 63, v15
	v_lshl_add_u32 v15, v15, 2, v4
	ds_read_b32 v15, v15
	v_add_u32_e32 v16, 8, v3
	v_and_b32_e32 v16, 63, v16
	v_lshl_add_u32 v16, v16, 2, v4
	ds_read_b32 v16, v16
	v_add_u32_e32 v17, 9, v3
	v_and_b32_e32 v17, 63, v17
	v_lshl_add_u32 v17, v17, 2, v4
	ds_read_b32 v17, v17
	v_add_u32_e32 v19, 10, v3
	v_and_b32_e32 v19, 63, v19
	v_lshl_add_u32 v19, v19, 2, v4
	ds_read_b32 v19, v19
	v_add_u32_e32 v20, 11, v3
	v_and_b32_e32 v20, 63, v20
	v_lshl_add_u32 v20, v20, 2, v4
	ds_read_b32 v20, v20
	v_add_u32_e32 v21, 12, v3
	v_and_b32_e32 v21, 63, v21
	v_lshl_add_u32 v21, v21, 2, v4
	ds_read_b32 v21, v21
	s_waitcnt lgkmcnt(10)
	v_fmac_f32_e32 v5, v6, v6
	s_waitcnt lgkmcnt(9)
	v_fmac_f32_e32 v5, v9, v9
	s_waitcnt lgkmcnt(8)
	v_fmac_f32_e32 v5, v12, v12
	s_waitcnt lgkmcnt(7)
	v_fmac_f32_e32 v5, v13, v13
	s_waitcnt lgkmcnt(6)
	v_fmac_f32_e32 v5, v14, v14
	s_waitcnt lgkmcnt(5)
	v_fmac_f32_e32 v5, v15, v15
	s_waitcnt lgkmcnt(4)
	v_fmac_f32_e32 v5, v16, v16
	s_waitcnt lgkmcnt(3)
	v_fmac_f32_e32 v5, v17, v17
	s_waitcnt lgkmcnt(2)
	v_fmac_f32_e32 v5, v19, v19
	s_waitcnt lgkmcnt(1)
	v_fmac_f32_e32 v5, v20, v20
	s_waitcnt lgkmcnt(0)
	v_fmac_f32_e32 v5, v21, v21
	v_add_u32_e32 v6, 13, v3
	v_and_b32_e32 v6, 63, v6
	v_lshl_add_u32 v6, v6, 2, v4
	ds_read_b32 v6, v6
	v_add_u32_e32 v9, 14, v3
	v_and_b32_e32 v9, 63, v9
	v_lshl_add_u32 v9, v9, 2, v4
	ds_read_b32 v9, v9
	v_add_u32_e32 v12, 15, v3
	v_and_b32_e32 v12, 63, v12
	v_lshl_add_u32 v12, v12, 2, v4
	ds_read_b32 v12, v12
	v_add_u32_e32 v13, 16, v3
	v_and_b32_e32 v13, 63, v13
	v_lshl_add_u32 v13, v13, 2, v4
	ds_read_b32 v13, v13
	v_add_u32_e32 v14, 17, v3
	v_and_b32_e32 v14, 63, v14
	v_lshl_add_u32 v14, v14, 2, v4
	ds_read_b32 v14, v14
	v_add_u32_e32 v15, 18, v3
	v_and_b32_e32 v15, 63, v15
	v_lshl_add_u32 v15, v15, 2, v4
	ds_read_b32 v15, v15
	v_add_u32_e32 v16, 19, v3
	v_and_b32_e32 v16, 63, v16
	v_lshl_add_u32 v16, v16, 2, v4
	ds_read_b32 v16, v16
	v_add_u32_e32 v17, 20, v3
	v_and_b32_e32 v17, 63, v17
	v_lshl_add_u32 v17, v17, 2, v4
	ds_read_b32 v17, v17
	v_add_u32_e32 v19, 21, v3
	v_and_b32_e32 v19, 63, v19
	v_lshl_add_u32 v19, v19, 2, v4
	ds_read_b32 v19, v19
	v_add_u32_e32 v20, 22, v3
	v_and_b32_e32 v20, 63, v20
	v_lshl_add_u32 v20, v20, 2, v4
	ds_read_b32 v20, v20
	v_add_u32_e32 v21, 23, v3
	v_and_b32_e32 v21, 63, v21
	v_lshl_add_u32 v21, v21, 2, v4
	ds_read_b32 v21, v21
	s_waitcnt lgkmcnt(10)
	v_fmac_f32_e32 v5, v6, v6
	s_waitcnt lgkmcnt(9)
	v_fmac_f32_e32 v5, v9, v9
	s_waitcnt lgkmcnt(8)
	v_fmac_f32_e32 v5, v12, v12
	s_waitcnt lgkmcnt(7)
	v_fmac_f32_e32 v5, v13, v13
	s_waitcnt lgkmcnt(6)
	v_fmac_f32_e32 v5, v14, v14
	s_waitcnt lgkmcnt(5)
	v_fmac_f32_e32 v5, v15, v15
	s_waitcnt lgkmcnt(4)
	v_fmac_f32_e32 v5, v16, v16
	s_waitcnt lgkmcnt(3)
	v_fmac_f32_e32 v5, v17, v17
	s_waitcnt lgkmcnt(2)
	v_fmac_f32_e32 v5, v19, v19
	s_waitcnt lgkmcnt(1)
	v_fmac_f32_e32 v5, v20, v20
	s_waitcnt lgkmcnt(0)
	v_fmac_f32_e32 v5, v21, v21
	v_add_u32_e32 v6, 24, v3
	v_and_b32_e32 v6, 63, v6
	v_lshl_add_u32 v6, v6, 2, v4
	ds_read_b32 v6, v6
	v_add_u32_e32 v9, 25, v3
	v_and_b32_e32 v9, 63, v9
	v_lshl_add_u32 v9, v9, 2, v4
	ds_read_b32 v9, v9
	v_add_u32_e32 v12, 26, v3
	v_and_b32_e32 v12, 63, v12
	v_lshl_add_u32 v12, v12, 2, v4
	ds_read_b32 v12, v12
	v_add_u32_e32 v13, 27, v3
	v_and_b32_e32 v13, 63, v13
	v_lshl_add_u32 v13, v13, 2, v4
	ds_read_b32 v13, v13
	v_add_u32_e32 v14, 28, v3
	v_and_b32_e32 v14, 63, v14
	v_lshl_add_u32 v14, v14, 2, v4
	ds_read_b32 v14, v14
	v_add_u32_e32 v15, 29, v3
	v_and_b32_e32 v15, 63, v15
	v_lshl_add_u32 v15, v15, 2, v4
	ds_read_b32 v15, v15
	v_add_u32_e32 v16, 30, v3
	v_and_b32_e32 v16, 63, v16
	v_lshl_add_u32 v16, v16, 2, v4
	ds_read_b32 v16, v16
	v_add_u32_e32 v17, 31, v3
	v_and_b32_e32 v17, 63, v17
	v_lshl_add_u32 v17, v17, 2, v4
	ds_read_b32 v17, v17
	v_bitop3_b32 v19, v3, 32, 63 bitop3:0x6c
	v_lshl_add_u32 v19, v19, 2, v4
	ds_read_b32 v19, v19
	v_add_u32_e32 v20, 33, v3
	v_and_b32_e32 v20, 63, v20
	v_lshl_add_u32 v20, v20, 2, v4
	ds_read_b32 v20, v20
	v_add_u32_e32 v21, 34, v3
	v_and_b32_e32 v21, 63, v21
	v_lshl_add_u32 v21, v21, 2, v4
	ds_read_b32 v21, v21
	s_waitcnt lgkmcnt(10)
	v_fmac_f32_e32 v5, v6, v6
	s_waitcnt lgkmcnt(9)
	v_fmac_f32_e32 v5, v9, v9
	s_waitcnt lgkmcnt(8)
	v_fmac_f32_e32 v5, v12, v12
	s_waitcnt lgkmcnt(7)
	v_fmac_f32_e32 v5, v13, v13
	s_waitcnt lgkmcnt(6)
	v_fmac_f32_e32 v5, v14, v14
	s_waitcnt lgkmcnt(5)
; #define TIDX (tid_launder())
; DI void epi_rownorm(const float* Ct, float* rn, int W) {
;   const int row = TIDX >> 1, grp = TIDX & 1;
;   float ss = 0.f;
;   for (int c0 = 0; c0 < 64; ++c0) { const int c = (c0 + row) & 63; const float v = Ct[row * 132 + grp * 64 + c]; ss += v * v; }
;   if (W == 128) { ss += __shfl_xor(ss, 1); ss *= 0.5f; }
;   rn[row * 2 + grp] = rsqrtf(ss * (1.f / 64.f) + 1e-6f);
;   __syncthreads();
; }
; DI void epi_storeKF(const float* Ct, int cb, const float* rn, int grp, const float* gain, bf16_t* dst) {
;   const int slot = TIDX, r = slot & 31, d0 = (slot >> 5) * 8;
;   float gq[8];
; #pragma unroll
;   for (int j = 0; j < 8; ++j) gq[j] = rn ? gain[d0 + j] : 1.f;
	v_fmac_f32_e32 v5, v15, v15
	s_waitcnt lgkmcnt(4)
	v_fmac_f32_e32 v5, v16, v16
	s_waitcnt lgkmcnt(3)
	v_fmac_f32_e32 v5, v17, v17
	s_waitcnt lgkmcnt(2)
	v_fmac_f32_e32 v5, v19, v19
	s_waitcnt lgkmcnt(1)
	v_fmac_f32_e32 v5, v20, v20
	s_waitcnt lgkmcnt(0)
	v_fmac_f32_e32 v5, v21, v21
	v_add_u32_e32 v6, 35, v3
	v_and_b32_e32 v6, 63, v6
	v_lshl_add_u32 v6, v6, 2, v4
	ds_read_b32 v6, v6
	v_add_u32_e32 v9, 36, v3
	v_and_b32_e32 v9, 63, v9
	v_lshl_add_u32 v9, v9, 2, v4
	ds_read_b32 v9, v9
	v_add_u32_e32 v12, 37, v3
	v_and_b32_e32 v12, 63, v12
	v_lshl_add_u32 v12, v12, 2, v4
	ds_read_b32 v12, v12
	v_add_u32_e32 v13, 38, v3
	v_and_b32_e32 v13, 63, v13
	v_lshl_add_u32 v13, v13, 2, v4
	ds_read_b32 v13, v13
	v_add_u32_e32 v14, 39, v3
	v_and_b32_e32 v14, 63, v14
	v_lshl_add_u32 v14, v14, 2, v4
	ds_read_b32 v14, v14
	v_add_u32_e32 v15, 40, v3
	v_and_b32_e32 v15, 63, v15
	v_lshl_add_u32 v15, v15, 2, v4
	ds_read_b32 v15, v15
	v_add_u32_e32 v16, 41, v3
	v_and_b32_e32 v16, 63, v16
	v_lshl_add_u32 v16, v16, 2, v4
	ds_read_b32 v16, v16
	v_add_u32_e32 v17, 42, v3
	v_and_b32_e32 v17, 63, v17
	v_lshl_add_u32 v17, v17, 2, v4
	ds_read_b32 v17, v17
	v_add_u32_e32 v19, 43, v3
	v_and_b32_e32 v19, 63, v19
	v_lshl_add_u32 v19, v19, 2, v4
	ds_read_b32 v19, v19
	v_add_u32_e32 v20, 44, v3
	v_and_b32_e32 v20, 63, v20
	v_lshl_add_u32 v20, v20, 2, v4
	ds_read_b32 v20, v20
	v_add_u32_e32 v21, 45, v3
	v_and_b32_e32 v21, 63, v21
	v_lshl_add_u32 v21, v21, 2, v4
	ds_read_b32 v21, v21
	s_waitcnt lgkmcnt(10)
	v_fmac_f32_e32 v5, v6, v6
	s_waitcnt lgkmcnt(9)
	v_fmac_f32_e32 v5, v9, v9
	s_waitcnt lgkmcnt(8)
	v_fmac_f32_e32 v5, v12, v12
	s_waitcnt lgkmcnt(7)
	v_fmac_f32_e32 v5, v13, v13
	s_waitcnt lgkmcnt(6)
	v_fmac_f32_e32 v5, v14, v14
	s_waitcnt lgkmcnt(5)
	v_fmac_f32_e32 v5, v15, v15
	s_waitcnt lgkmcnt(4)
	v_fmac_f32_e32 v5, v16, v16
	s_waitcnt lgkmcnt(3)
	v_fmac_f32_e32 v5, v17, v17
	s_waitcnt lgkmcnt(2)
	v_fmac_f32_e32 v5, v19, v19
	s_waitcnt lgkmcnt(1)
	v_fmac_f32_e32 v5, v20, v20
	s_waitcnt lgkmcnt(0)
	v_fmac_f32_e32 v5, v21, v21
	v_add_u32_e32 v6, 46, v3
	v_and_b32_e32 v6, 63, v6
	v_lshl_add_u32 v6, v6, 2, v4
	ds_read_b32 v6, v6
	v_add_u32_e32 v9, 47, v3
	v_and_b32_e32 v9, 63, v9
	v_lshl_add_u32 v9, v9, 2, v4
	ds_read_b32 v9, v9
	v_add_u32_e32 v12, 48, v3
	v_and_b32_e32 v12, 63, v12
	v_lshl_add_u32 v12, v12, 2, v4
	ds_read_b32 v12, v12
	v_add_u32_e32 v13, 49, v3
	v_and_b32_e32 v13, 63, v13
	v_lshl_add_u32 v13, v13, 2, v4
	ds_read_b32 v13, v13
	v_add_u32_e32 v14, 50, v3
	v_and_b32_e32 v14, 63, v14
	v_lshl_add_u32 v14, v14, 2, v4
	ds_read_b32 v14, v14
	v_add_u32_e32 v15, 51, v3
	v_and_b32_e32 v15, 63, v15
	v_lshl_add_u32 v15, v15, 2, v4
	ds_read_b32 v15, v15
	v_add_u32_e32 v16, 52, v3
	v_and_b32_e32 v16, 63, v16
	v_lshl_add_u32 v16, v16, 2, v4
	ds_read_b32 v16, v16
	v_add_u32_e32 v17, 53, v3
	v_and_b32_e32 v17, 63, v17
	v_lshl_add_u32 v17, v17, 2, v4
	ds_read_b32 v17, v17
	s_waitcnt lgkmcnt(7)
	v_fmac_f32_e32 v5, v6, v6
	s_waitcnt lgkmcnt(6)
	v_fmac_f32_e32 v5, v9, v9
	s_waitcnt lgkmcnt(5)
	v_fmac_f32_e32 v5, v12, v12
	s_waitcnt lgkmcnt(4)
	v_fmac_f32_e32 v5, v13, v13
	s_waitcnt lgkmcnt(3)
	v_fmac_f32_e32 v5, v14, v14
	s_waitcnt lgkmcnt(2)
	v_fmac_f32_e32 v5, v15, v15
	s_waitcnt lgkmcnt(1)
	v_fmac_f32_e32 v5, v16, v16
	s_waitcnt lgkmcnt(0)
	v_fmac_f32_e32 v5, v17, v17
	v_add_u32_e32 v6, 54, v3
	v_and_b32_e32 v6, 63, v6
	v_lshl_add_u32 v6, v6, 2, v4
	ds_read_b32 v6, v6
	s_waitcnt lgkmcnt(0)
	v_pk_mul_f32 v[6:7], v[6:7], v[6:7]
	s_nop 0
	v_add_f32_e32 v5, v5, v6
	v_add_f32_e32 v5, v5, v7
	v_add_u32_e32 v6, 56, v3
	v_add_u32_e32 v7, 57, v3
	v_and_b32_e32 v6, 63, v6
	v_and_b32_e32 v7, 63, v7
	v_lshl_add_u32 v6, v6, 2, v4
	v_lshl_add_u32 v7, v7, 2, v4
	ds_read_b32 v6, v6
	ds_read_b32 v7, v7
	s_waitcnt lgkmcnt(0)
	v_pk_mul_f32 v[6:7], v[6:7], v[6:7]
	s_nop 0
	v_add_f32_e32 v5, v5, v6
	v_add_f32_e32 v5, v5, v7
	v_add_u32_e32 v6, 58, v3
	v_add_u32_e32 v7, 59, v3
	v_and_b32_e32 v6, 63, v6
	v_and_b32_e32 v7, 63, v7
	v_lshl_add_u32 v6, v6, 2, v4
	v_lshl_add_u32 v7, v7, 2, v4
	ds_read_b32 v6, v6
	ds_read_b32 v7, v7
	s_waitcnt lgkmcnt(0)
	v_pk_mul_f32 v[6:7], v[6:7], v[6:7]
	s_nop 0
	v_add_f32_e32 v5, v5, v6
	v_add_f32_e32 v5, v5, v7
	v_add_u32_e32 v6, 60, v3
	v_add_u32_e32 v7, 61, v3
	v_and_b32_e32 v6, 63, v6
	v_and_b32_e32 v7, 63, v7
	v_lshl_add_u32 v6, v6, 2, v4
	v_lshl_add_u32 v7, v7, 2, v4
	ds_read_b32 v6, v6
	ds_read_b32 v7, v7
	s_waitcnt lgkmcnt(0)
	v_pk_mul_f32 v[6:7], v[6:7], v[6:7]
	s_nop 0
	v_add_f32_e32 v5, v5, v6
	v_add_f32_e32 v8, v5, v7
	v_add_u32_e32 v5, 62, v3
	v_add_u32_e32 v3, -1, v3
	v_and_b32_e32 v5, 63, v5
	v_and_b32_e32 v3, 63, v3
	v_lshl_add_u32 v5, v5, 2, v4
	v_lshl_add_u32 v3, v3, 2, v4
	ds_read_b32 v6, v5
	ds_read_b32 v7, v3
	s_waitcnt lgkmcnt(0)
	v_pk_mul_f32 v[4:5], v[6:7], v[6:7]
	s_nop 0
	v_add_f32_e32 v3, v8, v4
	v_add_f32_e32 v3, v3, v5
	v_fmamk_f32 v3, v3, 0x3c800000, v231
	v_cmp_gt_f32_e32 vcc, s0, v3
	v_mul_f32_e32 v4, 0x4b800000, v3
	s_mov_b32 s0, 0x3ffffffe
	v_cndmask_b32_e32 v3, v3, v4, vcc
	v_rsq_f32_e32 v3, v3
	v_and_or_b32 v0, v0, s0, v2
	v_lshl_add_u32 v0, v0, 2, v237
	v_mul_f32_e32 v4, 0x45800000, v3
	v_cndmask_b32_e32 v3, v3, v4, vcc
	ds_write_b32 v0, v3
	s_waitcnt lgkmcnt(0)
	s_barrier
	v_cndmask_b32_e64 v3, 0, 1, s[6:7]
	v_ashrrev_i32_e32 v0, 2, v18
	v_and_b32_e32 v2, -8, v0
	v_cmp_ne_u32_e64 s[0:1], 1, v3
	v_ashrrev_i32_e32 v3, 31, v2
	v_readlane_b32 s6, v254, 7
	v_readlane_b32 s7, v254, 8
	s_nop 1
	v_lshl_add_u64 v[4:5], v[2:3], 2, s[6:7]
	global_load_dword v10, v[4:5], off offset:512
	s_and_b64 vcc, exec, s[0:1]
	s_cbranch_vccnz .LBB0_1987
	v_readlane_b32 s6, v254, 7
	v_readlane_b32 s7, v254, 8
	s_nop 1
	v_lshl_add_u64 v[4:5], v[2:3], 2, s[6:7]
	global_load_dword v11, v[4:5], off offset:516

; #define TIDX (tid_launder())
; DI void epi_rownorm(const float* Ct, float* rn, int W) {
;   const int row = TIDX >> 1, grp = TIDX & 1;
;   float ss = 0.f;
;   for (int c0 = 0; c0 < 64; ++c0) { const int c = (c0 + row) & 63; const float v = Ct[row * 132 + grp * 64 + c]; ss += v * v; }
;   if (W == 128) { ss += __shfl_xor(ss, 1); ss *= 0.5f; }
;   rn[row * 2 + grp] = rsqrtf(ss * (1.f / 64.f) + 1e-6f);
;   __syncthreads();
; }
.LBB0_2012:
	s_andn2_b64 vcc, exec, s[0:1]
	s_cbranch_vccnz .LBB0_2041
	s_cmp_gt_i32 s12, 9
	s_mov_b64 s[0:1], -1
	s_cbranch_scc0 .LBB0_2039
	v_mov_b32_e32 v0, v230
	v_mov_b32_e32 v2, v230
	s_mov_b32 s0, 0x800000
	v_ashrrev_i32_e32 v3, 1, v0
	v_and_b32_e32 v2, 1, v2
	v_mul_lo_u32 v4, v3, s79
	v_add_u32_e32 v7, 55, v3
	v_lshl_add_u32 v4, v2, 8, v4
	v_and_b32_e32 v5, 63, v3
	v_and_b32_e32 v7, 63, v7
	v_lshl_add_u32 v5, v5, 2, v4
	v_lshl_add_u32 v7, v7, 2, v4
	ds_read_b32 v6, v5
	ds_read_b32 v7, v7
	v_add_u32_e32 v5, 1, v3
	v_and_b32_e32 v5, 63, v5
	v_lshl_add_u32 v5, v5, 2, v4
	ds_read_b32 v5, v5
	v_readlane_b32 s16, v252, 57
	v_readlane_b32 s24, v253, 1
	v_readlane_b32 s25, v253, 2
	v_mov_b32_e32 v18, v230
	s_waitcnt lgkmcnt(0)
	v_mul_f32_e32 v5, v5, v5
	v_fmac_f32_e32 v5, v6, v6
	v_add_u32_e32 v6, 2, v3
	v_and_b32_e32 v6, 63, v6
	v_lshl_add_u32 v6, v6, 2, v4
	ds_read_b32 v6, v6
	s_mov_b64 s[6:7], -1
	s_waitcnt vmcnt(4)
	v_mov_b32_e32 v11, 1.0
	v_mov_b32_e32 v10, 1.0
	v_readlane_b32 s17, v252, 58
	s_waitcnt lgkmcnt(0)
	v_fmac_f32_e32 v5, v6, v6
	v_add_u32_e32 v6, 3, v3
	v_and_b32_e32 v6, 63, v6
	v_lshl_add_u32 v6, v6, 2, v4
	ds_read_b32 v6, v6
	v_readlane_b32 s18, v252, 59
	v_readlane_b32 s19, v252, 60
	v_readlane_b32 s20, v252, 61
	v_readlane_b32 s21, v252, 62
	s_waitcnt lgkmcnt(0)
	v_fmac_f32_e32 v5, v6, v6
	v_add_u32_e32 v6, 4, v3
	v_and_b32_e32 v6, 63, v6
	v_lshl_add_u32 v6, v6, 2, v4
	ds_read_b32 v6, v6
	v_readlane_b32 s22, v252, 63
	v_readlane_b32 s23, v253, 0
	v_readlane_b32 s26, v253, 3
	v_readlane_b32 s27, v253, 4
	s_waitcnt lgkmcnt(0)
	v_fmac_f32_e32 v5, v6, v6
	v_add_u32_e32 v6, 5, v3
	v_and_b32_e32 v6, 63, v6
	v_lshl_add_u32 v6, v6, 2, v4
	ds_read_b32 v6, v6
	v_readlane_b32 s28, v253, 5
	v_readlane_b32 s29, v253, 6
	v_readlane_b32 s30, v253, 7
	v_readlane_b32 s31, v253, 8
	s_waitcnt lgkmcnt(0)
	v_fmac_f32_e32 v5, v6, v6
	v_add_u32_e32 v6, 6, v3
	v_and_b32_e32 v6, 63, v6
	v_lshl_add_u32 v6, v6, 2, v4
	ds_read_b32 v6, v6
	v_add_u32_e32 v8, 7, v3
	v_and_b32_e32 v8, 63, v8
	v_lshl_add_u32 v8, v8, 2, v4
	ds_read_b32 v8, v8
	v_add_u32_e32 v9, 8, v3
	v_and_b32_e32 v9, 63, v9
	v_lshl_add_u32 v9, v9, 2, v4
	ds_read_b32 v9, v9
	v_add_u32_e32 v12, 9, v3
	v_and_b32_e32 v12, 63, v12
	v_lshl_add_u32 v12, v12, 2, v4
	ds_read_b32 v12, v12
	v_add_u32_e32 v13, 10, v3
	v_and_b32_e32 v13, 63, v13
	v_lshl_add_u32 v13, v13, 2, v4
	ds_read_b32 v13, v13
	v_add_u32_e32 v14, 11, v3
	v_and_b32_e32 v14, 63, v14
	v_lshl_add_u32 v14, v14, 2, v4
	ds_read_b32 v14, v14
	v_add_u32_e32 v15, 12, v3
	v_and_b32_e32 v15, 63, v15
	v_lshl_add_u32 v15, v15, 2, v4
	ds_read_b32 v15, v15
	v_add_u32_e32 v16, 13, v3
	v_and_b32_e32 v16, 63, v16
	v_lshl_add_u32 v16, v16, 2, v4
	ds_read_b32 v16, v16
	v_add_u32_e32 v17, 14, v3
	v_and_b32_e32 v17, 63, v17
	v_lshl_add_u32 v17, v17, 2, v4
	ds_read_b32 v17, v17
	v_add_u32_e32 v19, 15, v3
	v_and_b32_e32 v19, 63, v19
	v_lshl_add_u32 v19, v19, 2, v4
	ds_read_b32 v19, v19
	v_add_u32_e32 v20, 16, v3
	v_and_b32_e32 v20, 63, v20
	v_lshl_add_u32 v20, v20, 2, v4
	ds_read_b32 v20, v20
	v_add_u32_e32 v21, 17, v3
	v_and_b32_e32 v21, 63, v21
	v_lshl_add_u32 v21, v21, 2, v4
	ds_read_b32 v21, v21
	v_add_u32_e32 v72, 18, v3
	v_and_b32_e32 v72, 63, v72
	v_lshl_add_u32 v72, v72, 2, v4
	ds_read_b32 v72, v72
	s_waitcnt lgkmcnt(12)
	v_fmac_f32_e32 v5, v6, v6
	s_waitcnt lgkmcnt(11)
	v_fmac_f32_e32 v5, v8, v8
	s_waitcnt lgkmcnt(10)
	v_fmac_f32_e32 v5, v9, v9
	s_waitcnt lgkmcnt(9)
	v_fmac_f32_e32 v5, v12, v12
	s_waitcnt lgkmcnt(8)
	v_fmac_f32_e32 v5, v13, v13
	s_waitcnt lgkmcnt(7)
	v_fmac_f32_e32 v5, v14, v14
	s_waitcnt lgkmcnt(6)
	v_fmac_f32_e32 v5, v15, v15
	s_waitcnt lgkmcnt(5)
	v_fmac_f32_e32 v5, v16, v16
	s_waitcnt lgkmcnt(4)
	v_fmac_f32_e32 v5, v17, v17
	s_waitcnt lgkmcnt(3)
	v_fmac_f32_e32 v5, v19, v19
	s_waitcnt lgkmcnt(2)
	v_fmac_f32_e32 v5, v20, v20
	s_waitcnt lgkmcnt(1)
	v_fmac_f32_e32 v5, v21, v21
	s_waitcnt lgkmcnt(0)
	v_fmac_f32_e32 v5, v72, v72
	v_add_u32_e32 v6, 19, v3
	v_and_b32_e32 v6, 63, v6
	v_lshl_add_u32 v6, v6, 2, v4
	ds_read_b32 v6, v6
	v_add_u32_e32 v8, 20, v3
	v_and_b32_e32 v8, 63, v8
	v_lshl_add_u32 v8, v8, 2, v4
	ds_read_b32 v8, v8
	v_add_u32_e32 v9, 21, v3
	v_and_b32_e32 v9, 63, v9
	v_lshl_add_u32 v9, v9, 2, v4
	ds_read_b32 v9, v9
	v_add_u32_e32 v12, 22, v3
	v_and_b32_e32 v12, 63, v12
	v_lshl_add_u32 v12, v12, 2, v4
	ds_read_b32 v12, v12
	v_add_u32_e32 v13, 23, v3
	v_and_b32_e32 v13, 63, v13
	v_lshl_add_u32 v13, v13, 2, v4
	ds_read_b32 v13, v13
	v_add_u32_e32 v14, 24, v3
	v_and_b32_e32 v14, 63, v14
	v_lshl_add_u32 v14, v14, 2, v4
	ds_read_b32 v14, v14
	v_add_u32_e32 v15, 25, v3
	v_and_b32_e32 v15, 63, v15
	v_lshl_add_u32 v15, v15, 2, v4
	ds_read_b32 v15, v15
	v_add_u32_e32 v16, 26, v3
	v_and_b32_e32 v16, 63, v16
	v_lshl_add_u32 v16, v16, 2, v4
	ds_read_b32 v16, v16
	v_add_u32_e32 v17, 27, v3
	v_and_b32_e32 v17, 63, v17
	v_lshl_add_u32 v17, v17, 2, v4
	ds_read_b32 v17, v17
	v_add_u32_e32 v19, 28, v3
	v_and_b32_e32 v19, 63, v19
	v_lshl_add_u32 v19, v19, 2, v4
	ds_read_b32 v19, v19
	v_add_u32_e32 v20, 29, v3
	v_and_b32_e32 v20, 63, v20
	v_lshl_add_u32 v20, v20, 2, v4
	ds_read_b32 v20, v20
	v_add_u32_e32 v21, 30, v3
	v_and_b32_e32 v21, 63, v21
	v_lshl_add_u32 v21, v21, 2, v4
	ds_read_b32 v21, v21
	v_add_u32_e32 v72, 31, v3
	v_and_b32_e32 v72, 63, v72
	v_lshl_add_u32 v72, v72, 2, v4
	ds_read_b32 v72, v72
	s_waitcnt lgkmcnt(12)
	v_fmac_f32_e32 v5, v6, v6
	s_waitcnt lgkmcnt(11)
	v_fmac_f32_e32 v5, v8, v8
	s_waitcnt lgkmcnt(10)
	v_fmac_f32_e32 v5, v9, v9
	s_waitcnt lgkmcnt(9)
	v_fmac_f32_e32 v5, v12, v12
	s_waitcnt lgkmcnt(8)
	v_fmac_f32_e32 v5, v13, v13
	s_waitcnt lgkmcnt(7)
	v_fmac_f32_e32 v5, v14, v14
	s_waitcnt lgkmcnt(6)
; #define TIDX (tid_launder())
; DI void epi_rownorm(const float* Ct, float* rn, int W) {
;   const int row = TIDX >> 1, grp = TIDX & 1;
;   float ss = 0.f;
;   for (int c0 = 0; c0 < 64; ++c0) { const int c = (c0 + row) & 63; const float v = Ct[row * 132 + grp * 64 + c]; ss += v * v; }
;   if (W == 128) { ss += __shfl_xor(ss, 1); ss *= 0.5f; }
;   rn[row * 2 + grp] = rsqrtf(ss * (1.f / 64.f) + 1e-6f);
;   __syncthreads();
; }
	v_fmac_f32_e32 v5, v15, v15
	s_waitcnt lgkmcnt(5)
	v_fmac_f32_e32 v5, v16, v16
	s_waitcnt lgkmcnt(4)
	v_fmac_f32_e32 v5, v17, v17
	s_waitcnt lgkmcnt(3)
	v_fmac_f32_e32 v5, v19, v19
	s_waitcnt lgkmcnt(2)
	v_fmac_f32_e32 v5, v20, v20
	s_waitcnt lgkmcnt(1)
	v_fmac_f32_e32 v5, v21, v21
	s_waitcnt lgkmcnt(0)
	v_fmac_f32_e32 v5, v72, v72
	v_bitop3_b32 v6, v3, 32, 63 bitop3:0x6c
	v_lshl_add_u32 v6, v6, 2, v4
	ds_read_b32 v6, v6
	v_add_u32_e32 v8, 33, v3
	v_and_b32_e32 v8, 63, v8
	v_lshl_add_u32 v8, v8, 2, v4
	ds_read_b32 v8, v8
	v_add_u32_e32 v9, 34, v3
	v_and_b32_e32 v9, 63, v9
	v_lshl_add_u32 v9, v9, 2, v4
	ds_read_b32 v9, v9
	v_add_u32_e32 v12, 35, v3
	v_and_b32_e32 v12, 63, v12
	v_lshl_add_u32 v12, v12, 2, v4
	ds_read_b32 v12, v12
	v_add_u32_e32 v13, 36, v3
	v_and_b32_e32 v13, 63, v13
	v_lshl_add_u32 v13, v13, 2, v4
	ds_read_b32 v13, v13
	v_add_u32_e32 v14, 37, v3
	v_and_b32_e32 v14, 63, v14
	v_lshl_add_u32 v14, v14, 2, v4
	ds_read_b32 v14, v14
	v_add_u32_e32 v15, 38, v3
	v_and_b32_e32 v15, 63, v15
	v_lshl_add_u32 v15, v15, 2, v4
	ds_read_b32 v15, v15
	v_add_u32_e32 v16, 39, v3
	v_and_b32_e32 v16, 63, v16
	v_lshl_add_u32 v16, v16, 2, v4
	ds_read_b32 v16, v16
	v_add_u32_e32 v17, 40, v3
	v_and_b32_e32 v17, 63, v17
	v_lshl_add_u32 v17, v17, 2, v4
	ds_read_b32 v17, v17
	v_add_u32_e32 v19, 41, v3
	v_and_b32_e32 v19, 63, v19
	v_lshl_add_u32 v19, v19, 2, v4
	ds_read_b32 v19, v19
	v_add_u32_e32 v20, 42, v3
	v_and_b32_e32 v20, 63, v20
	v_lshl_add_u32 v20, v20, 2, v4
	ds_read_b32 v20, v20
	v_add_u32_e32 v21, 43, v3
	v_and_b32_e32 v21, 63, v21
	v_lshl_add_u32 v21, v21, 2, v4
	ds_read_b32 v21, v21
	v_add_u32_e32 v72, 44, v3
	v_and_b32_e32 v72, 63, v72
	v_lshl_add_u32 v72, v72, 2, v4
	ds_read_b32 v72, v72
	s_waitcnt lgkmcnt(12)
	v_fmac_f32_e32 v5, v6, v6
	s_waitcnt lgkmcnt(11)
	v_fmac_f32_e32 v5, v8, v8
	s_waitcnt lgkmcnt(10)
	v_fmac_f32_e32 v5, v9, v9
	s_waitcnt lgkmcnt(9)
	v_fmac_f32_e32 v5, v12, v12
	s_waitcnt lgkmcnt(8)
	v_fmac_f32_e32 v5, v13, v13
	s_waitcnt lgkmcnt(7)
	v_fmac_f32_e32 v5, v14, v14
	s_waitcnt lgkmcnt(6)
	v_fmac_f32_e32 v5, v15, v15
	s_waitcnt lgkmcnt(5)
	v_fmac_f32_e32 v5, v16, v16
	s_waitcnt lgkmcnt(4)
	v_fmac_f32_e32 v5, v17, v17
	s_waitcnt lgkmcnt(3)
	v_fmac_f32_e32 v5, v19, v19
	s_waitcnt lgkmcnt(2)
	v_fmac_f32_e32 v5, v20, v20
	s_waitcnt lgkmcnt(1)
	v_fmac_f32_e32 v5, v21, v21
	s_waitcnt lgkmcnt(0)
	v_fmac_f32_e32 v5, v72, v72
	v_add_u32_e32 v6, 45, v3
	v_and_b32_e32 v6, 63, v6
	v_lshl_add_u32 v6, v6, 2, v4
	ds_read_b32 v6, v6
	v_add_u32_e32 v8, 46, v3
	v_and_b32_e32 v8, 63, v8
	v_lshl_add_u32 v8, v8, 2, v4
	ds_read_b32 v8, v8
	v_add_u32_e32 v9, 47, v3
	v_and_b32_e32 v9, 63, v9
	v_lshl_add_u32 v9, v9, 2, v4
	ds_read_b32 v9, v9
	v_add_u32_e32 v12, 48, v3
	v_and_b32_e32 v12, 63, v12
	v_lshl_add_u32 v12, v12, 2, v4
	ds_read_b32 v12, v12
	v_add_u32_e32 v13, 49, v3
	v_and_b32_e32 v13, 63, v13
	v_lshl_add_u32 v13, v13, 2, v4
	ds_read_b32 v13, v13
	v_add_u32_e32 v14, 50, v3
	v_and_b32_e32 v14, 63, v14
	v_lshl_add_u32 v14, v14, 2, v4
	ds_read_b32 v14, v14
	v_add_u32_e32 v15, 51, v3
	v_and_b32_e32 v15, 63, v15
	v_lshl_add_u32 v15, v15, 2, v4
	ds_read_b32 v15, v15
	v_add_u32_e32 v16, 52, v3
	v_and_b32_e32 v16, 63, v16
	v_lshl_add_u32 v16, v16, 2, v4
	ds_read_b32 v16, v16
	v_add_u32_e32 v17, 53, v3
	v_and_b32_e32 v17, 63, v17
	v_lshl_add_u32 v17, v17, 2, v4
	ds_read_b32 v17, v17
	s_waitcnt lgkmcnt(8)
	v_fmac_f32_e32 v5, v6, v6
	s_waitcnt lgkmcnt(7)
	v_fmac_f32_e32 v5, v8, v8
	s_waitcnt lgkmcnt(6)
	v_fmac_f32_e32 v5, v9, v9
	s_waitcnt lgkmcnt(5)
	v_fmac_f32_e32 v5, v12, v12
	s_waitcnt lgkmcnt(4)
	v_fmac_f32_e32 v5, v13, v13
	s_waitcnt lgkmcnt(3)
	v_fmac_f32_e32 v5, v14, v14
	s_waitcnt lgkmcnt(2)
	v_fmac_f32_e32 v5, v15, v15
	s_waitcnt lgkmcnt(1)
	v_fmac_f32_e32 v5, v16, v16
	s_waitcnt lgkmcnt(0)
	v_fmac_f32_e32 v5, v17, v17
	v_add_u32_e32 v6, 54, v3
	v_and_b32_e32 v6, 63, v6
	v_lshl_add_u32 v6, v6, 2, v4
	ds_read_b32 v6, v6
	s_waitcnt lgkmcnt(0)
	v_pk_mul_f32 v[6:7], v[6:7], v[6:7]
	s_nop 0
	v_add_f32_e32 v5, v5, v6
	v_add_f32_e32 v5, v5, v7
	v_add_u32_e32 v6, 56, v3
	v_add_u32_e32 v7, 57, v3
	v_and_b32_e32 v6, 63, v6
	v_and_b32_e32 v7, 63, v7
	v_lshl_add_u32 v6, v6, 2, v4
	v_lshl_add_u32 v7, v7, 2, v4
	ds_read_b32 v6, v6
	ds_read_b32 v7, v7
	s_waitcnt lgkmcnt(0)
	v_pk_mul_f32 v[6:7], v[6:7], v[6:7]
	s_nop 0
	v_add_f32_e32 v5, v5, v6
	v_add_f32_e32 v5, v5, v7
	v_add_u32_e32 v6, 58, v3
	v_add_u32_e32 v7, 59, v3
	v_and_b32_e32 v6, 63, v6
	v_and_b32_e32 v7, 63, v7
	v_lshl_add_u32 v6, v6, 2, v4
	v_lshl_add_u32 v7, v7, 2, v4
	ds_read_b32 v6, v6
	ds_read_b32 v7, v7
	s_waitcnt lgkmcnt(0)
	v_pk_mul_f32 v[6:7], v[6:7], v[6:7]
	s_nop 0
	v_add_f32_e32 v5, v5, v6
	v_add_f32_e32 v5, v5, v7
	v_add_u32_e32 v6, 60, v3
	v_add_u32_e32 v7, 61, v3
	v_and_b32_e32 v6, 63, v6
	v_and_b32_e32 v7, 63, v7
	v_lshl_add_u32 v6, v6, 2, v4
	v_lshl_add_u32 v7, v7, 2, v4
	ds_read_b32 v6, v6
	ds_read_b32 v7, v7
	s_waitcnt lgkmcnt(0)
	v_pk_mul_f32 v[6:7], v[6:7], v[6:7]
	s_nop 0
	v_add_f32_e32 v5, v5, v6
	v_add_f32_e32 v8, v5, v7
	v_add_u32_e32 v5, 62, v3
	v_add_u32_e32 v3, -1, v3
	v_and_b32_e32 v5, 63, v5
	v_and_b32_e32 v3, 63, v3
	v_lshl_add_u32 v5, v5, 2, v4
	v_lshl_add_u32 v3, v3, 2, v4
	ds_read_b32 v6, v5
	ds_read_b32 v7, v3
	s_waitcnt lgkmcnt(0)
	v_pk_mul_f32 v[4:5], v[6:7], v[6:7]
	s_nop 0
	v_add_f32_e32 v3, v8, v4
	v_add_f32_e32 v3, v3, v5
	v_fmamk_f32 v3, v3, 0x3c800000, v231
	v_cmp_gt_f32_e32 vcc, s0, v3
	v_mul_f32_e32 v4, 0x4b800000, v3
	s_mov_b32 s0, 0x3ffffffe
	v_cndmask_b32_e32 v3, v3, v4, vcc
	v_rsq_f32_e32 v3, v3
	v_and_or_b32 v0, v0, s0, v2
	v_lshl_add_u32 v0, v0, 2, v237
	v_mul_f32_e32 v4, 0x45800000, v3
	v_cndmask_b32_e32 v3, v3, v4, vcc
	ds_write_b32 v0, v3
	v_mov_b32_e32 v0, v230
	s_waitcnt lgkmcnt(0)
	s_barrier
; #define TIDX (tid_launder())
; DI unsigned pack2(float a, float b) { hwf2 v = {a, b}; hwbf2 r = __builtin_convertvector(v, hwbf2); return __builtin_bit_cast(unsigned, r); }
; DI float siluf(float x) { return x * __builtin_amdgcn_rcpf(1.f + __expf(-x)); }
; DI void epi_store64(const float* Ct, int cb, const float* rn, int grp, const float* gain, bool silu, const float* bias,
;                     bf16_t* dst, size_t ldd, int dcol0, int m0, int Mmax) {
;   const int tid = TIDX, c = (tid & 15) * 4;
;   float4 gv = make_float4(1.f, 1.f, 1.f, 1.f), bv = make_float4(0.f, 0.f, 0.f, 0.f);
;   if (rn) gv = *(const float4*)(gain + c);
;   if (bias) bv = *(const float4*)(bias + c);
; #pragma unroll
;   for (int q = 0; q < 8; ++q) {
;     const int row = (tid >> 4) + 16 * q;
;     float4 v = *(const float4*)(Ct + row * 132 + cb + c);
;     v.x += bv.x; v.y += bv.y; v.z += bv.z; v.w += bv.w;
;     if (rn) { const float sc = rn[row * 2 + grp]; v.x *= sc * gv.x; v.y *= sc * gv.y; v.z *= sc * gv.z; v.w *= sc * gv.w; }
;     if (silu) { v.x = siluf(v.x); v.y = siluf(v.y); v.z = siluf(v.z); v.w = siluf(v.w); }
;     uint2 o; o.x = pack2(v.x, v.y); o.y = pack2(v.z, v.w);
;     *(uint2*)(dst + (size_t)(m0 + row) * ldd + dcol0 + c) = o;
;   }
; }
; DI void epi_storeKF(const float* Ct, int cb, const float* rn, int grp, const float* gain, bf16_t* dst) {
;   const int slot = TIDX, r = slot & 31, d0 = (slot >> 5) * 8;
;   float gq[8];
; #pragma unroll
;   for (int j = 0; j < 8; ++j) gq[j] = rn ? gain[d0 + j] : 1.f;
	s_andn2_b64 vcc, exec, s[6:7]
	v_lshlrev_b32_e32 v2, 2, v0
	v_and_b32_e32 v4, 60, v2
	v_ashrrev_i32_e32 v8, 4, v0
	v_lshlrev_b32_e32 v0, 1, v4
	v_lshl_add_u64 v[2:3], s[24:25], 0, v[0:1]
	v_mul_lo_u32 v0, v8, s79
	v_lshl_add_u32 v0, v4, 2, v0
	ds_read_b128 v[72:75], v0
	ds_read_b128 v[76:79], v0 offset:8448
	ds_read_b128 v[80:83], v0 offset:16896
	ds_read_b128 v[84:87], v0 offset:25344
	ds_read_b128 v[88:91], v0 offset:33792
	ds_read_b128 v[92:95], v0 offset:42240
	ds_read_b128 v[96:99], v0 offset:50688
	ds_read_b128 v[100:103], v0 offset:59136
	v_add_u32_e32 v8, s11, v8
	s_waitcnt lgkmcnt(7)
	v_pk_add_f32 v[4:5], v[72:73], 0 op_sel_hi:[1, 0]
	v_pk_add_f32 v[6:7], v[74:75], 0 op_sel_hi:[1, 0]
	v_cvt_pk_bf16_f32 v4, v4, v5
	v_cvt_pk_bf16_f32 v5, v6, v7
	v_mad_i64_i32 v[6:7], s[0:1], v8, s50, v[2:3]
	global_store_dwordx2 v[6:7], v[4:5], off offset:2560
	s_waitcnt lgkmcnt(6)
	v_pk_add_f32 v[4:5], v[76:77], 0 op_sel_hi:[1, 0]
	v_pk_add_f32 v[6:7], v[78:79], 0 op_sel_hi:[1, 0]
	v_cvt_pk_bf16_f32 v4, v4, v5
	v_cvt_pk_bf16_f32 v5, v6, v7
	v_add_u32_e32 v6, 16, v8
	v_mad_i64_i32 v[6:7], s[0:1], v6, s50, v[2:3]
	global_store_dwordx2 v[6:7], v[4:5], off offset:2560
	s_waitcnt lgkmcnt(5)
	v_pk_add_f32 v[4:5], v[80:81], 0 op_sel_hi:[1, 0]
	v_pk_add_f32 v[6:7], v[82:83], 0 op_sel_hi:[1, 0]
	v_cvt_pk_bf16_f32 v4, v4, v5
	v_cvt_pk_bf16_f32 v5, v6, v7
	v_add_u32_e32 v6, 32, v8
	v_mad_i64_i32 v[6:7], s[0:1], v6, s50, v[2:3]
	global_store_dwordx2 v[6:7], v[4:5], off offset:2560
	s_waitcnt lgkmcnt(4)
	v_pk_add_f32 v[4:5], v[84:85], 0 op_sel_hi:[1, 0]
	v_pk_add_f32 v[6:7], v[86:87], 0 op_sel_hi:[1, 0]
	v_cvt_pk_bf16_f32 v4, v4, v5
	v_cvt_pk_bf16_f32 v5, v6, v7
	v_add_u32_e32 v6, 48, v8
	v_mad_i64_i32 v[6:7], s[0:1], v6, s50, v[2:3]
	global_store_dwordx2 v[6:7], v[4:5], off offset:2560
	s_waitcnt lgkmcnt(3)
	v_pk_add_f32 v[4:5], v[88:89], 0 op_sel_hi:[1, 0]
	v_pk_add_f32 v[6:7], v[90:91], 0 op_sel_hi:[1, 0]
	v_cvt_pk_bf16_f32 v4, v4, v5
	v_cvt_pk_bf16_f32 v5, v6, v7
	v_add_u32_e32 v6, 64, v8
	v_mad_i64_i32 v[6:7], s[0:1], v6, s50, v[2:3]
	global_store_dwordx2 v[6:7], v[4:5], off offset:2560
	s_waitcnt lgkmcnt(2)
	v_pk_add_f32 v[4:5], v[92:93], 0 op_sel_hi:[1, 0]
	v_pk_add_f32 v[6:7], v[94:95], 0 op_sel_hi:[1, 0]
	v_cvt_pk_bf16_f32 v4, v4, v5
	v_cvt_pk_bf16_f32 v5, v6, v7
	v_add_u32_e32 v6, 0x50, v8
	v_mad_i64_i32 v[6:7], s[0:1], v6, s50, v[2:3]
	global_store_dwordx2 v[6:7], v[4:5], off offset:2560
	s_waitcnt lgkmcnt(1)
	v_pk_add_f32 v[4:5], v[96:97], 0 op_sel_hi:[1, 0]
	v_pk_add_f32 v[6:7], v[98:99], 0 op_sel_hi:[1, 0]
	v_cvt_pk_bf16_f32 v4, v4, v5
	v_cvt_pk_bf16_f32 v5, v6, v7
	v_add_u32_e32 v6, 0x60, v8
	v_mad_i64_i32 v[6:7], s[0:1], v6, s50, v[2:3]
	global_store_dwordx2 v[6:7], v[4:5], off offset:2560
	v_add_u32_e32 v0, 0x70, v8
	v_mad_i64_i32 v[2:3], s[0:1], v0, s50, v[2:3]
	s_waitcnt lgkmcnt(0)
	v_pk_add_f32 v[4:5], v[100:101], 0 op_sel_hi:[1, 0]
	v_pk_add_f32 v[6:7], v[102:103], 0 op_sel_hi:[1, 0]
	v_cvt_pk_bf16_f32 v4, v4, v5
	v_cvt_pk_bf16_f32 v5, v6, v7
	global_store_dwordx2 v[2:3], v[4:5], off offset:2560
	v_cndmask_b32_e64 v3, 0, 1, s[6:7]
	v_ashrrev_i32_e32 v0, 2, v18
	v_and_b32_e32 v2, -8, v0
	v_cmp_ne_u32_e64 s[0:1], 1, v3
	v_ashrrev_i32_e32 v3, 31, v2
	s_cbranch_vccnz .LBB0_2016
	v_readlane_b32 s6, v254, 7
	v_readlane_b32 s7, v254, 8
	s_nop 1
	v_lshl_add_u64 v[4:5], v[2:3], 2, s[6:7]
	global_load_dword v10, v[4:5], off offset:256

; #define TIDX (tid_launder())
; DI void epi_rownorm(const float* Ct, float* rn, int W) {
;   const int row = TIDX >> 1, grp = TIDX & 1;
;   float ss = 0.f;
;   for (int c0 = 0; c0 < 64; ++c0) { const int c = (c0 + row) & 63; const float v = Ct[row * 132 + grp * 64 + c]; ss += v * v; }
;   if (W == 128) { ss += __shfl_xor(ss, 1); ss *= 0.5f; }
;   rn[row * 2 + grp] = rsqrtf(ss * (1.f / 64.f) + 1e-6f);
;   __syncthreads();
; }
.LBB0_2045:
	s_andn2_b64 vcc, exec, s[0:1]
	s_cbranch_vccnz .LBB0_2085
	v_mov_b32_e32 v0, v230
	v_mov_b32_e32 v2, v230
	s_mov_b32 s0, 0x800000
	v_ashrrev_i32_e32 v3, 1, v0
	v_and_b32_e32 v2, 1, v2
	v_mul_lo_u32 v4, v3, s79
	v_add_u32_e32 v7, 57, v3
	v_lshl_add_u32 v4, v2, 8, v4
	v_and_b32_e32 v5, 63, v3
	v_and_b32_e32 v7, 63, v7
	v_lshl_add_u32 v5, v5, 2, v4
	v_lshl_add_u32 v7, v7, 2, v4
	ds_read_b32 v6, v5
	ds_read_b32 v7, v7
	v_add_u32_e32 v5, 1, v3
	v_and_b32_e32 v5, 63, v5
	v_lshl_add_u32 v5, v5, 2, v4
	ds_read_b32 v5, v5
	s_mov_b64 s[4:5], -1
	s_waitcnt lgkmcnt(0)
	v_mul_f32_e32 v5, v5, v5
	v_fmac_f32_e32 v5, v6, v6
	v_add_u32_e32 v6, 2, v3
	v_and_b32_e32 v6, 63, v6
	v_lshl_add_u32 v6, v6, 2, v4
	ds_read_b32 v6, v6
	v_add_u32_e32 v9, 3, v3
	v_and_b32_e32 v9, 63, v9
	v_lshl_add_u32 v9, v9, 2, v4
	ds_read_b32 v9, v9
	v_add_u32_e32 v10, 4, v3
	v_and_b32_e32 v10, 63, v10
	v_lshl_add_u32 v10, v10, 2, v4
	ds_read_b32 v10, v10
	v_add_u32_e32 v11, 5, v3
	v_and_b32_e32 v11, 63, v11
	v_lshl_add_u32 v11, v11, 2, v4
	ds_read_b32 v11, v11
	v_add_u32_e32 v12, 6, v3
	v_and_b32_e32 v12, 63, v12
	v_lshl_add_u32 v12, v12, 2, v4
	ds_read_b32 v12, v12
	v_add_u32_e32 v13, 7, v3
	v_and_b32_e32 v13, 63, v13
	v_lshl_add_u32 v13, v13, 2, v4
	ds_read_b32 v13, v13
	v_add_u32_e32 v14, 8, v3
	v_and_b32_e32 v14, 63, v14
	v_lshl_add_u32 v14, v14, 2, v4
	ds_read_b32 v14, v14
	v_add_u32_e32 v15, 9, v3
	v_and_b32_e32 v15, 63, v15
	v_lshl_add_u32 v15, v15, 2, v4
	ds_read_b32 v15, v15
	v_add_u32_e32 v16, 10, v3
	v_and_b32_e32 v16, 63, v16
	v_lshl_add_u32 v16, v16, 2, v4
	ds_read_b32 v16, v16
	v_add_u32_e32 v17, 11, v3
	v_and_b32_e32 v17, 63, v17
	v_lshl_add_u32 v17, v17, 2, v4
	ds_read_b32 v17, v17
	s_waitcnt lgkmcnt(9)
	v_fmac_f32_e32 v5, v6, v6
	s_waitcnt lgkmcnt(8)
	v_fmac_f32_e32 v5, v9, v9
	s_waitcnt lgkmcnt(7)
	v_fmac_f32_e32 v5, v10, v10
	s_waitcnt lgkmcnt(6)
	v_fmac_f32_e32 v5, v11, v11
	s_waitcnt lgkmcnt(5)
	v_fmac_f32_e32 v5, v12, v12
	s_waitcnt lgkmcnt(4)
	v_fmac_f32_e32 v5, v13, v13
	s_waitcnt lgkmcnt(3)
	v_fmac_f32_e32 v5, v14, v14
	s_waitcnt lgkmcnt(2)
	v_fmac_f32_e32 v5, v15, v15
	s_waitcnt lgkmcnt(1)
	v_fmac_f32_e32 v5, v16, v16
	s_waitcnt lgkmcnt(0)
	v_fmac_f32_e32 v5, v17, v17
	v_add_u32_e32 v6, 12, v3
	v_and_b32_e32 v6, 63, v6
	v_lshl_add_u32 v6, v6, 2, v4
	ds_read_b32 v6, v6
	v_add_u32_e32 v9, 13, v3
	v_and_b32_e32 v9, 63, v9
	v_lshl_add_u32 v9, v9, 2, v4
	ds_read_b32 v9, v9
	v_add_u32_e32 v10, 14, v3
	v_and_b32_e32 v10, 63, v10
	v_lshl_add_u32 v10, v10, 2, v4
	ds_read_b32 v10, v10
	v_add_u32_e32 v11, 15, v3
	v_and_b32_e32 v11, 63, v11
	v_lshl_add_u32 v11, v11, 2, v4
	ds_read_b32 v11, v11
	v_add_u32_e32 v12, 16, v3
	v_and_b32_e32 v12, 63, v12
	v_lshl_add_u32 v12, v12, 2, v4
	ds_read_b32 v12, v12
	v_add_u32_e32 v13, 17, v3
	v_and_b32_e32 v13, 63, v13
	v_lshl_add_u32 v13, v13, 2, v4
	ds_read_b32 v13, v13
	v_add_u32_e32 v14, 18, v3
	v_and_b32_e32 v14, 63, v14
	v_lshl_add_u32 v14, v14, 2, v4
	ds_read_b32 v14, v14
	v_add_u32_e32 v15, 19, v3
	v_and_b32_e32 v15, 63, v15
	v_lshl_add_u32 v15, v15, 2, v4
	ds_read_b32 v15, v15
	v_add_u32_e32 v16, 20, v3
	v_and_b32_e32 v16, 63, v16
	v_lshl_add_u32 v16, v16, 2, v4
	ds_read_b32 v16, v16
	v_add_u32_e32 v17, 21, v3
	v_and_b32_e32 v17, 63, v17
	v_lshl_add_u32 v17, v17, 2, v4
	ds_read_b32 v17, v17
	s_waitcnt lgkmcnt(9)
	v_fmac_f32_e32 v5, v6, v6
	s_waitcnt lgkmcnt(8)
	v_fmac_f32_e32 v5, v9, v9
	s_waitcnt lgkmcnt(7)
	v_fmac_f32_e32 v5, v10, v10
	s_waitcnt lgkmcnt(6)
	v_fmac_f32_e32 v5, v11, v11
	s_waitcnt lgkmcnt(5)
	v_fmac_f32_e32 v5, v12, v12
	s_waitcnt lgkmcnt(4)
	v_fmac_f32_e32 v5, v13, v13
	s_waitcnt lgkmcnt(3)
	v_fmac_f32_e32 v5, v14, v14
	s_waitcnt lgkmcnt(2)
	v_fmac_f32_e32 v5, v15, v15
	s_waitcnt lgkmcnt(1)
	v_fmac_f32_e32 v5, v16, v16
	s_waitcnt lgkmcnt(0)
	v_fmac_f32_e32 v5, v17, v17
	v_add_u32_e32 v6, 22, v3
	v_and_b32_e32 v6, 63, v6
	v_lshl_add_u32 v6, v6, 2, v4
	ds_read_b32 v6, v6
	v_add_u32_e32 v9, 23, v3
	v_and_b32_e32 v9, 63, v9
	v_lshl_add_u32 v9, v9, 2, v4
	ds_read_b32 v9, v9
	v_add_u32_e32 v10, 24, v3
	v_and_b32_e32 v10, 63, v10
	v_lshl_add_u32 v10, v10, 2, v4
	ds_read_b32 v10, v10
	v_add_u32_e32 v11, 25, v3
	v_and_b32_e32 v11, 63, v11
	v_lshl_add_u32 v11, v11, 2, v4
	ds_read_b32 v11, v11
	v_add_u32_e32 v12, 26, v3
	v_and_b32_e32 v12, 63, v12
	v_lshl_add_u32 v12, v12, 2, v4
	ds_read_b32 v12, v12
	v_add_u32_e32 v13, 27, v3
	v_and_b32_e32 v13, 63, v13
	v_lshl_add_u32 v13, v13, 2, v4
	ds_read_b32 v13, v13
	v_add_u32_e32 v14, 28, v3
	v_and_b32_e32 v14, 63, v14
	v_lshl_add_u32 v14, v14, 2, v4
	ds_read_b32 v14, v14
	v_add_u32_e32 v15, 29, v3
	v_and_b32_e32 v15, 63, v15
	v_lshl_add_u32 v15, v15, 2, v4
	ds_read_b32 v15, v15
	v_add_u32_e32 v16, 30, v3
	v_and_b32_e32 v16, 63, v16
	v_lshl_add_u32 v16, v16, 2, v4
	ds_read_b32 v16, v16
	v_add_u32_e32 v17, 31, v3
	v_and_b32_e32 v17, 63, v17
	v_lshl_add_u32 v17, v17, 2, v4
	ds_read_b32 v17, v17
	s_waitcnt lgkmcnt(9)
	v_fmac_f32_e32 v5, v6, v6
	s_waitcnt lgkmcnt(8)
	v_fmac_f32_e32 v5, v9, v9
	s_waitcnt lgkmcnt(7)
	v_fmac_f32_e32 v5, v10, v10
	s_waitcnt lgkmcnt(6)
	v_fmac_f32_e32 v5, v11, v11
	s_waitcnt lgkmcnt(5)
	v_fmac_f32_e32 v5, v12, v12
	s_waitcnt lgkmcnt(4)
	v_fmac_f32_e32 v5, v13, v13
	s_waitcnt lgkmcnt(3)
	v_fmac_f32_e32 v5, v14, v14
	s_waitcnt lgkmcnt(2)
	v_fmac_f32_e32 v5, v15, v15
	s_waitcnt lgkmcnt(1)
	v_fmac_f32_e32 v5, v16, v16
	s_waitcnt lgkmcnt(0)
; #define TIDX (tid_launder())
; DI void epi_rownorm(const float* Ct, float* rn, int W) {
;   const int row = TIDX >> 1, grp = TIDX & 1;
;   float ss = 0.f;
;   for (int c0 = 0; c0 < 64; ++c0) { const int c = (c0 + row) & 63; const float v = Ct[row * 132 + grp * 64 + c]; ss += v * v; }
;   if (W == 128) { ss += __shfl_xor(ss, 1); ss *= 0.5f; }
;   rn[row * 2 + grp] = rsqrtf(ss * (1.f / 64.f) + 1e-6f);
;   __syncthreads();
; }
; DI void epi_store64(const float* Ct, int cb, const float* rn, int grp, const float* gain, bool silu, const float* bias,
;                     bf16_t* dst, size_t ldd, int dcol0, int m0, int Mmax) {
;   const int tid = TIDX, c = (tid & 15) * 4;
;   float4 gv = make_float4(1.f, 1.f, 1.f, 1.f), bv = make_float4(0.f, 0.f, 0.f, 0.f);
;   if (rn) gv = *(const float4*)(gain + c);
	v_fmac_f32_e32 v5, v17, v17
	v_bitop3_b32 v6, v3, 32, 63 bitop3:0x6c
	v_lshl_add_u32 v6, v6, 2, v4
	ds_read_b32 v6, v6
	v_add_u32_e32 v9, 33, v3
	v_and_b32_e32 v9, 63, v9
	v_lshl_add_u32 v9, v9, 2, v4
	ds_read_b32 v9, v9
	v_add_u32_e32 v10, 34, v3
	v_and_b32_e32 v10, 63, v10
	v_lshl_add_u32 v10, v10, 2, v4
	ds_read_b32 v10, v10
	v_add_u32_e32 v11, 35, v3
	v_and_b32_e32 v11, 63, v11
	v_lshl_add_u32 v11, v11, 2, v4
	ds_read_b32 v11, v11
	v_add_u32_e32 v12, 36, v3
	v_and_b32_e32 v12, 63, v12
	v_lshl_add_u32 v12, v12, 2, v4
	ds_read_b32 v12, v12
	v_add_u32_e32 v13, 37, v3
	v_and_b32_e32 v13, 63, v13
	v_lshl_add_u32 v13, v13, 2, v4
	ds_read_b32 v13, v13
	v_add_u32_e32 v14, 38, v3
	v_and_b32_e32 v14, 63, v14
	v_lshl_add_u32 v14, v14, 2, v4
	ds_read_b32 v14, v14
	v_add_u32_e32 v15, 39, v3
	v_and_b32_e32 v15, 63, v15
	v_lshl_add_u32 v15, v15, 2, v4
	ds_read_b32 v15, v15
	v_add_u32_e32 v16, 40, v3
	v_and_b32_e32 v16, 63, v16
	v_lshl_add_u32 v16, v16, 2, v4
	ds_read_b32 v16, v16
	v_add_u32_e32 v17, 41, v3
	v_and_b32_e32 v17, 63, v17
	v_lshl_add_u32 v17, v17, 2, v4
	ds_read_b32 v17, v17
	s_waitcnt lgkmcnt(9)
	v_fmac_f32_e32 v5, v6, v6
	s_waitcnt lgkmcnt(8)
	v_fmac_f32_e32 v5, v9, v9
	s_waitcnt lgkmcnt(7)
	v_fmac_f32_e32 v5, v10, v10
	s_waitcnt lgkmcnt(6)
	v_fmac_f32_e32 v5, v11, v11
	s_waitcnt lgkmcnt(5)
	v_fmac_f32_e32 v5, v12, v12
	s_waitcnt lgkmcnt(4)
	v_fmac_f32_e32 v5, v13, v13
	s_waitcnt lgkmcnt(3)
	v_fmac_f32_e32 v5, v14, v14
	s_waitcnt lgkmcnt(2)
	v_fmac_f32_e32 v5, v15, v15
	s_waitcnt lgkmcnt(1)
	v_fmac_f32_e32 v5, v16, v16
	s_waitcnt lgkmcnt(0)
	v_fmac_f32_e32 v5, v17, v17
	v_add_u32_e32 v6, 42, v3
	v_and_b32_e32 v6, 63, v6
	v_lshl_add_u32 v6, v6, 2, v4
	ds_read_b32 v6, v6
	v_add_u32_e32 v9, 43, v3
	v_and_b32_e32 v9, 63, v9
	v_lshl_add_u32 v9, v9, 2, v4
	ds_read_b32 v9, v9
	v_add_u32_e32 v10, 44, v3
	v_and_b32_e32 v10, 63, v10
	v_lshl_add_u32 v10, v10, 2, v4
	ds_read_b32 v10, v10
	v_add_u32_e32 v11, 45, v3
	v_and_b32_e32 v11, 63, v11
	v_lshl_add_u32 v11, v11, 2, v4
	ds_read_b32 v11, v11
	v_add_u32_e32 v12, 46, v3
	v_and_b32_e32 v12, 63, v12
	v_lshl_add_u32 v12, v12, 2, v4
	ds_read_b32 v12, v12
	v_add_u32_e32 v13, 47, v3
	v_and_b32_e32 v13, 63, v13
	v_lshl_add_u32 v13, v13, 2, v4
	ds_read_b32 v13, v13
	v_add_u32_e32 v14, 48, v3
	v_and_b32_e32 v14, 63, v14
	v_lshl_add_u32 v14, v14, 2, v4
	ds_read_b32 v14, v14
	v_add_u32_e32 v15, 49, v3
	v_and_b32_e32 v15, 63, v15
	v_lshl_add_u32 v15, v15, 2, v4
	ds_read_b32 v15, v15
	v_add_u32_e32 v16, 50, v3
	v_and_b32_e32 v16, 63, v16
	v_lshl_add_u32 v16, v16, 2, v4
	ds_read_b32 v16, v16
	v_add_u32_e32 v17, 51, v3
	v_and_b32_e32 v17, 63, v17
	v_lshl_add_u32 v17, v17, 2, v4
	ds_read_b32 v17, v17
	s_waitcnt lgkmcnt(9)
	v_fmac_f32_e32 v5, v6, v6
	s_waitcnt lgkmcnt(8)
	v_fmac_f32_e32 v5, v9, v9
	s_waitcnt lgkmcnt(7)
	v_fmac_f32_e32 v5, v10, v10
	s_waitcnt lgkmcnt(6)
	v_fmac_f32_e32 v5, v11, v11
	s_waitcnt lgkmcnt(5)
	v_fmac_f32_e32 v5, v12, v12
	s_waitcnt lgkmcnt(4)
	v_fmac_f32_e32 v5, v13, v13
	s_waitcnt lgkmcnt(3)
	v_fmac_f32_e32 v5, v14, v14
	s_waitcnt lgkmcnt(2)
	v_fmac_f32_e32 v5, v15, v15
	s_waitcnt lgkmcnt(1)
	v_fmac_f32_e32 v5, v16, v16
	s_waitcnt lgkmcnt(0)
	v_fmac_f32_e32 v5, v17, v17
	v_add_u32_e32 v6, 52, v3
	v_and_b32_e32 v6, 63, v6
	v_lshl_add_u32 v6, v6, 2, v4
	ds_read_b32 v6, v6
	v_add_u32_e32 v9, 53, v3
	v_and_b32_e32 v9, 63, v9
	v_lshl_add_u32 v9, v9, 2, v4
	ds_read_b32 v9, v9
	v_add_u32_e32 v10, 54, v3
	v_and_b32_e32 v10, 63, v10
	v_lshl_add_u32 v10, v10, 2, v4
	ds_read_b32 v10, v10
	v_add_u32_e32 v11, 55, v3
	v_and_b32_e32 v11, 63, v11
	v_lshl_add_u32 v11, v11, 2, v4
	ds_read_b32 v11, v11
	s_waitcnt lgkmcnt(3)
	v_fmac_f32_e32 v5, v6, v6
	s_waitcnt lgkmcnt(2)
	v_fmac_f32_e32 v5, v9, v9
	s_waitcnt lgkmcnt(1)
	v_fmac_f32_e32 v5, v10, v10
	s_waitcnt lgkmcnt(0)
	v_fmac_f32_e32 v5, v11, v11
	v_add_u32_e32 v6, 56, v3
	v_and_b32_e32 v6, 63, v6
	v_lshl_add_u32 v6, v6, 2, v4
	ds_read_b32 v6, v6
	s_waitcnt lgkmcnt(0)
	v_pk_mul_f32 v[6:7], v[6:7], v[6:7]
	s_nop 0
	v_add_f32_e32 v5, v5, v6
	v_add_f32_e32 v5, v5, v7
	v_add_u32_e32 v6, 58, v3
	v_add_u32_e32 v7, 59, v3
	v_and_b32_e32 v6, 63, v6
	v_and_b32_e32 v7, 63, v7
	v_lshl_add_u32 v6, v6, 2, v4
	v_lshl_add_u32 v7, v7, 2, v4
	ds_read_b32 v6, v6
	ds_read_b32 v7, v7
	s_waitcnt lgkmcnt(0)
	v_pk_mul_f32 v[6:7], v[6:7], v[6:7]
	s_nop 0
	v_add_f32_e32 v5, v5, v6
	v_add_f32_e32 v5, v5, v7
	v_add_u32_e32 v6, 60, v3
	v_add_u32_e32 v7, 61, v3
	v_and_b32_e32 v6, 63, v6
	v_and_b32_e32 v7, 63, v7
	v_lshl_add_u32 v6, v6, 2, v4
	v_lshl_add_u32 v7, v7, 2, v4
	ds_read_b32 v6, v6
	ds_read_b32 v7, v7
	s_waitcnt lgkmcnt(0)
	v_pk_mul_f32 v[6:7], v[6:7], v[6:7]
	s_nop 0
	v_add_f32_e32 v5, v5, v6
	v_add_f32_e32 v8, v5, v7
	v_add_u32_e32 v5, 62, v3
	v_add_u32_e32 v3, -1, v3
	v_and_b32_e32 v5, 63, v5
	v_and_b32_e32 v3, 63, v3
	v_lshl_add_u32 v5, v5, 2, v4
	v_lshl_add_u32 v3, v3, 2, v4
	ds_read_b32 v6, v5
	ds_read_b32 v7, v3
	s_waitcnt lgkmcnt(0)
	v_pk_mul_f32 v[4:5], v[6:7], v[6:7]
	s_nop 0
	v_add_f32_e32 v3, v8, v4
	v_add_f32_e32 v3, v3, v5
	v_and_b32_e32 v5, 64, v249
	v_xor_b32_e32 v4, 1, v249
	v_add_u32_e32 v5, 64, v5
	v_cmp_lt_i32_e32 vcc, v4, v5
	v_mov_b32_e32 v6, v230
	s_nop 0
	v_cndmask_b32_e32 v4, v249, v4, vcc
	v_lshlrev_b32_e32 v4, 2, v4
	ds_bpermute_b32 v4, v4, v3
	s_waitcnt lgkmcnt(0)
	v_add_f32_e32 v3, v3, v4
	v_mul_f32_e32 v3, 0.5, v3
	v_fmamk_f32 v3, v3, 0x3c800000, v231
	v_cmp_gt_f32_e32 vcc, s0, v3
	v_mul_f32_e32 v4, 0x4b800000, v3
	s_mov_b32 s0, 0x3ffffffe
	v_cndmask_b32_e32 v3, v3, v4, vcc
	v_rsq_f32_e32 v3, v3
	v_and_or_b32 v0, v0, s0, v2
	v_lshl_add_u32 v0, v0, 2, v237
	v_cndmask_b32_e64 v2, 0, 1, s[4:5]
	v_mul_f32_e32 v4, 0x45800000, v3
	v_cndmask_b32_e32 v3, v3, v4, vcc
	ds_write_b32 v0, v3
	s_waitcnt lgkmcnt(0)
	s_barrier
	v_cmp_ne_u32_e64 s[0:1], 1, v2
	v_lshlrev_b32_e32 v0, 2, v6
	v_and_b32_e32 v0, 60, v0
	v_lshlrev_b32_e32 v7, 2, v0
	global_load_dwordx4 v[2:5], v7, s[72:73]
	s_branch .LBB0_2049
	v_mov_b32_e32 v4, 1.0
	v_mov_b32_e32 v5, v4
	v_mov_b32_e32 v2, v4
	v_mov_b32_e32 v3, v4

; #define TIDX (tid_launder())
; DI void epi_rownorm(const float* Ct, float* rn, int W) {
;   const int row = TIDX >> 1, grp = TIDX & 1;
;   float ss = 0.f;
;   for (int c0 = 0; c0 < 64; ++c0) { const int c = (c0 + row) & 63; const float v = Ct[row * 132 + grp * 64 + c]; ss += v * v; }
;   if (W == 128) { ss += __shfl_xor(ss, 1); ss *= 0.5f; }
;   rn[row * 2 + grp] = rsqrtf(ss * (1.f / 64.f) + 1e-6f);
; DI void inproj_tile(const Params& p, int l, int mt, int tn, char* smem) {
;     ...
;   if (tn <= 3) {
;     epi_rownorm(Ct, rn, 64);
;     const float* g = tn < 2 ? p.a_q_norm + l * 64 : p.c_q_norm + l * 64;
.LBB0_2086:
	s_andn2_b64 vcc, exec, s[0:1]
	s_cbranch_vccnz .LBB0_1954
	v_mov_b32_e32 v0, v230
	v_mov_b32_e32 v2, v230
	s_mov_b32 s0, 0x800000
	v_ashrrev_i32_e32 v3, 1, v0
	v_and_b32_e32 v2, 1, v2
	v_mul_lo_u32 v4, v3, s79
	v_add_u32_e32 v7, 55, v3
	v_lshl_add_u32 v4, v2, 8, v4
	v_and_b32_e32 v5, 63, v3
	v_and_b32_e32 v7, 63, v7
	v_lshl_add_u32 v5, v5, 2, v4
	v_lshl_add_u32 v7, v7, 2, v4
	ds_read_b32 v6, v5
	ds_read_b32 v7, v7
	v_add_u32_e32 v5, 1, v3
	v_and_b32_e32 v5, 63, v5
	v_lshl_add_u32 v5, v5, 2, v4
	ds_read_b32 v5, v5
	v_readlane_b32 s16, v250, 2
	v_readlane_b32 s52, v250, 18
	v_readlane_b32 s17, v250, 3
	v_readlane_b32 s18, v250, 4
	s_waitcnt lgkmcnt(0)
	v_mul_f32_e32 v5, v5, v5
	v_fmac_f32_e32 v5, v6, v6
	v_add_u32_e32 v6, 2, v3
	v_and_b32_e32 v6, 63, v6
	v_lshl_add_u32 v6, v6, 2, v4
	ds_read_b32 v6, v6
	v_readlane_b32 s19, v250, 5
	v_readlane_b32 s20, v250, 6
	v_readlane_b32 s21, v250, 7
	v_readlane_b32 s22, v250, 8
	s_waitcnt lgkmcnt(0)
	v_fmac_f32_e32 v5, v6, v6
	v_add_u32_e32 v6, 3, v3
	v_and_b32_e32 v6, 63, v6
	v_lshl_add_u32 v6, v6, 2, v4
	ds_read_b32 v6, v6
	v_readlane_b32 s23, v250, 9
	v_readlane_b32 s24, v250, 10
	v_readlane_b32 s25, v250, 11
	v_readlane_b32 s53, v250, 19
	s_waitcnt lgkmcnt(0)
	v_fmac_f32_e32 v5, v6, v6
	v_add_u32_e32 v6, 4, v3
	v_and_b32_e32 v6, 63, v6
	v_lshl_add_u32 v6, v6, 2, v4
	ds_read_b32 v6, v6
	v_readlane_b32 s54, v250, 20
	v_readlane_b32 s55, v250, 21
	v_readlane_b32 s56, v250, 22
	v_readlane_b32 s57, v250, 23
	s_waitcnt lgkmcnt(0)
	v_fmac_f32_e32 v5, v6, v6
	v_add_u32_e32 v6, 5, v3
	v_and_b32_e32 v6, 63, v6
	v_lshl_add_u32 v6, v6, 2, v4
	ds_read_b32 v6, v6
	v_readlane_b32 s58, v250, 24
	v_readlane_b32 s59, v250, 25
	v_readlane_b32 s60, v250, 26
	v_readlane_b32 s61, v250, 27
	s_waitcnt lgkmcnt(0)
	v_fmac_f32_e32 v5, v6, v6
	v_add_u32_e32 v6, 6, v3
	v_and_b32_e32 v6, 63, v6
	v_lshl_add_u32 v6, v6, 2, v4
	ds_read_b32 v6, v6
	s_mov_b64 s[16:17], s[52:53]
	s_cmp_lt_i32 s12, 2
	v_readlane_b32 s26, v250, 12
	v_readlane_b32 s27, v250, 13
	s_waitcnt lgkmcnt(0)
	v_fmac_f32_e32 v5, v6, v6
	v_add_u32_e32 v6, 7, v3
	v_and_b32_e32 v6, 63, v6
	v_lshl_add_u32 v6, v6, 2, v4
	ds_read_b32 v6, v6
	s_mov_b64 s[22:23], s[58:59]
	s_cselect_b32 s3, s27, s23
	s_cselect_b32 s4, s26, s22
	s_mov_b64 s[6:7], -1
	s_waitcnt lgkmcnt(0)
	v_fmac_f32_e32 v5, v6, v6
	v_add_u32_e32 v6, 8, v3
	v_and_b32_e32 v6, 63, v6
	v_lshl_add_u32 v6, v6, 2, v4
	ds_read_b32 v6, v6
	v_readlane_b32 s28, v250, 14
	v_readlane_b32 s29, v250, 15
	v_readlane_b32 s30, v250, 16
	v_readlane_b32 s31, v250, 17
	s_waitcnt lgkmcnt(0)
	v_fmac_f32_e32 v5, v6, v6
	v_add_u32_e32 v6, 9, v3
	v_and_b32_e32 v6, 63, v6
	v_lshl_add_u32 v6, v6, 2, v4
	ds_read_b32 v6, v6
	v_readlane_b32 s62, v250, 28
	v_readlane_b32 s63, v250, 29
	v_readlane_b32 s64, v250, 30
	v_readlane_b32 s65, v250, 31
	s_waitcnt lgkmcnt(0)
	v_fmac_f32_e32 v5, v6, v6
	v_add_u32_e32 v6, 10, v3
	v_and_b32_e32 v6, 63, v6
	v_lshl_add_u32 v6, v6, 2, v4
	ds_read_b32 v6, v6
	v_readlane_b32 s66, v250, 32
	v_readlane_b32 s67, v250, 33
	s_mov_b64 s[18:19], s[54:55]
	s_mov_b64 s[20:21], s[56:57]
	s_waitcnt lgkmcnt(0)
	v_fmac_f32_e32 v5, v6, v6
	v_add_u32_e32 v6, 11, v3
	v_and_b32_e32 v6, 63, v6
	v_lshl_add_u32 v6, v6, 2, v4
	ds_read_b32 v6, v6
	s_mov_b64 s[24:25], s[60:61]
	s_waitcnt lgkmcnt(0)
	v_fmac_f32_e32 v5, v6, v6
	v_add_u32_e32 v6, 12, v3
	v_and_b32_e32 v6, 63, v6
	v_lshl_add_u32 v6, v6, 2, v4
	ds_read_b32 v6, v6
	v_add_u32_e32 v8, 13, v3
	v_and_b32_e32 v8, 63, v8
	v_lshl_add_u32 v8, v8, 2, v4
	ds_read_b32 v8, v8
	v_add_u32_e32 v9, 14, v3
	v_and_b32_e32 v9, 63, v9
	v_lshl_add_u32 v9, v9, 2, v4
	ds_read_b32 v9, v9
	v_add_u32_e32 v10, 15, v3
	v_and_b32_e32 v10, 63, v10
	v_lshl_add_u32 v10, v10, 2, v4
	ds_read_b32 v10, v10
	v_add_u32_e32 v11, 16, v3
	v_and_b32_e32 v11, 63, v11
	v_lshl_add_u32 v11, v11, 2, v4
	ds_read_b32 v11, v11
	v_add_u32_e32 v12, 17, v3
	v_and_b32_e32 v12, 63, v12
	v_lshl_add_u32 v12, v12, 2, v4
	ds_read_b32 v12, v12
	v_add_u32_e32 v13, 18, v3
	v_and_b32_e32 v13, 63, v13
	v_lshl_add_u32 v13, v13, 2, v4
	ds_read_b32 v13, v13
	v_add_u32_e32 v14, 19, v3
	v_and_b32_e32 v14, 63, v14
	v_lshl_add_u32 v14, v14, 2, v4
	ds_read_b32 v14, v14
	v_add_u32_e32 v15, 20, v3
	v_and_b32_e32 v15, 63, v15
	v_lshl_add_u32 v15, v15, 2, v4
	ds_read_b32 v15, v15
	v_add_u32_e32 v16, 21, v3
	v_and_b32_e32 v16, 63, v16
	v_lshl_add_u32 v16, v16, 2, v4
	ds_read_b32 v16, v16
	v_add_u32_e32 v17, 22, v3
	v_and_b32_e32 v17, 63, v17
	v_lshl_add_u32 v17, v17, 2, v4
	ds_read_b32 v17, v17
	s_waitcnt lgkmcnt(10)
	v_fmac_f32_e32 v5, v6, v6
	s_waitcnt lgkmcnt(9)
	v_fmac_f32_e32 v5, v8, v8
	s_waitcnt lgkmcnt(8)
	v_fmac_f32_e32 v5, v9, v9
	s_waitcnt lgkmcnt(7)
	v_fmac_f32_e32 v5, v10, v10
	s_waitcnt lgkmcnt(6)
	v_fmac_f32_e32 v5, v11, v11
	s_waitcnt lgkmcnt(5)
	v_fmac_f32_e32 v5, v12, v12
	s_waitcnt lgkmcnt(4)
	v_fmac_f32_e32 v5, v13, v13
	s_waitcnt lgkmcnt(3)
	v_fmac_f32_e32 v5, v14, v14
	s_waitcnt lgkmcnt(2)
	v_fmac_f32_e32 v5, v15, v15
	s_waitcnt lgkmcnt(1)
	v_fmac_f32_e32 v5, v16, v16
	s_waitcnt lgkmcnt(0)
	v_fmac_f32_e32 v5, v17, v17
	v_add_u32_e32 v6, 23, v3
	v_and_b32_e32 v6, 63, v6
	v_lshl_add_u32 v6, v6, 2, v4
	ds_read_b32 v6, v6
	v_add_u32_e32 v8, 24, v3
	v_and_b32_e32 v8, 63, v8
	v_lshl_add_u32 v8, v8, 2, v4
	ds_read_b32 v8, v8
	v_add_u32_e32 v9, 25, v3
	v_and_b32_e32 v9, 63, v9
	v_lshl_add_u32 v9, v9, 2, v4
	ds_read_b32 v9, v9
	v_add_u32_e32 v10, 26, v3
	v_and_b32_e32 v10, 63, v10
	v_lshl_add_u32 v10, v10, 2, v4
	ds_read_b32 v10, v10
	v_add_u32_e32 v11, 27, v3
	v_and_b32_e32 v11, 63, v11
	v_lshl_add_u32 v11, v11, 2, v4
	ds_read_b32 v11, v11
	v_add_u32_e32 v12, 28, v3
	v_and_b32_e32 v12, 63, v12
	v_lshl_add_u32 v12, v12, 2, v4
	ds_read_b32 v12, v12
	v_add_u32_e32 v13, 29, v3
	v_and_b32_e32 v13, 63, v13
	v_lshl_add_u32 v13, v13, 2, v4
	ds_read_b32 v13, v13
	v_add_u32_e32 v14, 30, v3
	v_and_b32_e32 v14, 63, v14
	v_lshl_add_u32 v14, v14, 2, v4
	ds_read_b32 v14, v14
	v_add_u32_e32 v15, 31, v3
	v_and_b32_e32 v15, 63, v15
	v_lshl_add_u32 v15, v15, 2, v4
	ds_read_b32 v15, v15
	v_bitop3_b32 v16, v3, 32, 63 bitop3:0x6c
	v_lshl_add_u32 v16, v16, 2, v4
	ds_read_b32 v16, v16
	v_add_u32_e32 v17, 33, v3
	v_and_b32_e32 v17, 63, v17
	v_lshl_add_u32 v17, v17, 2, v4
	ds_read_b32 v17, v17
	s_waitcnt lgkmcnt(10)
; #define TIDX (tid_launder())
; DI void epi_rownorm(const float* Ct, float* rn, int W) {
;   const int row = TIDX >> 1, grp = TIDX & 1;
;   float ss = 0.f;
;   for (int c0 = 0; c0 < 64; ++c0) { const int c = (c0 + row) & 63; const float v = Ct[row * 132 + grp * 64 + c]; ss += v * v; }
;   if (W == 128) { ss += __shfl_xor(ss, 1); ss *= 0.5f; }
;   rn[row * 2 + grp] = rsqrtf(ss * (1.f / 64.f) + 1e-6f);
;   __syncthreads();
; }
; DI void epi_store64(const float* Ct, int cb, const float* rn, int grp, const float* gain, bool silu, const float* bias,
;                     bf16_t* dst, size_t ldd, int dcol0, int m0, int Mmax) {
;   const int tid = TIDX, c = (tid & 15) * 4;
;   float4 gv = make_float4(1.f, 1.f, 1.f, 1.f), bv = make_float4(0.f, 0.f, 0.f, 0.f);
;   if (rn) gv = *(const float4*)(gain + c);
; DI void inproj_tile(const Params& p, int l, int mt, int tn, char* smem) {
;     ...
;     const float* g = tn < 2 ? p.a_q_norm + l * 64 : p.c_q_norm + l * 64;
;     epi_store64(Ct, 0, rn, 0, g, false, nullptr, p.projA, LDA_A, tn * 128, m0, T_TOK);
	v_fmac_f32_e32 v5, v6, v6
	s_waitcnt lgkmcnt(9)
	v_fmac_f32_e32 v5, v8, v8
	s_waitcnt lgkmcnt(8)
	v_fmac_f32_e32 v5, v9, v9
	s_waitcnt lgkmcnt(7)
	v_fmac_f32_e32 v5, v10, v10
	s_waitcnt lgkmcnt(6)
	v_fmac_f32_e32 v5, v11, v11
	s_waitcnt lgkmcnt(5)
	v_fmac_f32_e32 v5, v12, v12
	s_waitcnt lgkmcnt(4)
	v_fmac_f32_e32 v5, v13, v13
	s_waitcnt lgkmcnt(3)
	v_fmac_f32_e32 v5, v14, v14
	s_waitcnt lgkmcnt(2)
	v_fmac_f32_e32 v5, v15, v15
	s_waitcnt lgkmcnt(1)
	v_fmac_f32_e32 v5, v16, v16
	s_waitcnt lgkmcnt(0)
	v_fmac_f32_e32 v5, v17, v17
	v_add_u32_e32 v6, 34, v3
	v_and_b32_e32 v6, 63, v6
	v_lshl_add_u32 v6, v6, 2, v4
	ds_read_b32 v6, v6
	v_add_u32_e32 v8, 35, v3
	v_and_b32_e32 v8, 63, v8
	v_lshl_add_u32 v8, v8, 2, v4
	ds_read_b32 v8, v8
	v_add_u32_e32 v9, 36, v3
	v_and_b32_e32 v9, 63, v9
	v_lshl_add_u32 v9, v9, 2, v4
	ds_read_b32 v9, v9
	v_add_u32_e32 v10, 37, v3
	v_and_b32_e32 v10, 63, v10
	v_lshl_add_u32 v10, v10, 2, v4
	ds_read_b32 v10, v10
	v_add_u32_e32 v11, 38, v3
	v_and_b32_e32 v11, 63, v11
	v_lshl_add_u32 v11, v11, 2, v4
	ds_read_b32 v11, v11
	v_add_u32_e32 v12, 39, v3
	v_and_b32_e32 v12, 63, v12
	v_lshl_add_u32 v12, v12, 2, v4
	ds_read_b32 v12, v12
	v_add_u32_e32 v13, 40, v3
	v_and_b32_e32 v13, 63, v13
	v_lshl_add_u32 v13, v13, 2, v4
	ds_read_b32 v13, v13
	v_add_u32_e32 v14, 41, v3
	v_and_b32_e32 v14, 63, v14
	v_lshl_add_u32 v14, v14, 2, v4
	ds_read_b32 v14, v14
	v_add_u32_e32 v15, 42, v3
	v_and_b32_e32 v15, 63, v15
	v_lshl_add_u32 v15, v15, 2, v4
	ds_read_b32 v15, v15
	v_add_u32_e32 v16, 43, v3
	v_and_b32_e32 v16, 63, v16
	v_lshl_add_u32 v16, v16, 2, v4
	ds_read_b32 v16, v16
	v_add_u32_e32 v17, 44, v3
	v_and_b32_e32 v17, 63, v17
	v_lshl_add_u32 v17, v17, 2, v4
	ds_read_b32 v17, v17
	s_waitcnt lgkmcnt(10)
	v_fmac_f32_e32 v5, v6, v6
	s_waitcnt lgkmcnt(9)
	v_fmac_f32_e32 v5, v8, v8
	s_waitcnt lgkmcnt(8)
	v_fmac_f32_e32 v5, v9, v9
	s_waitcnt lgkmcnt(7)
	v_fmac_f32_e32 v5, v10, v10
	s_waitcnt lgkmcnt(6)
	v_fmac_f32_e32 v5, v11, v11
	s_waitcnt lgkmcnt(5)
	v_fmac_f32_e32 v5, v12, v12
	s_waitcnt lgkmcnt(4)
	v_fmac_f32_e32 v5, v13, v13
	s_waitcnt lgkmcnt(3)
	v_fmac_f32_e32 v5, v14, v14
	s_waitcnt lgkmcnt(2)
	v_fmac_f32_e32 v5, v15, v15
	s_waitcnt lgkmcnt(1)
	v_fmac_f32_e32 v5, v16, v16
	s_waitcnt lgkmcnt(0)
	v_fmac_f32_e32 v5, v17, v17
	v_add_u32_e32 v6, 45, v3
	v_and_b32_e32 v6, 63, v6
	v_lshl_add_u32 v6, v6, 2, v4
	ds_read_b32 v6, v6
	v_add_u32_e32 v8, 46, v3
	v_and_b32_e32 v8, 63, v8
	v_lshl_add_u32 v8, v8, 2, v4
	ds_read_b32 v8, v8
	v_add_u32_e32 v9, 47, v3
	v_and_b32_e32 v9, 63, v9
	v_lshl_add_u32 v9, v9, 2, v4
	ds_read_b32 v9, v9
	v_add_u32_e32 v10, 48, v3
	v_and_b32_e32 v10, 63, v10
	v_lshl_add_u32 v10, v10, 2, v4
	ds_read_b32 v10, v10
	v_add_u32_e32 v11, 49, v3
	v_and_b32_e32 v11, 63, v11
	v_lshl_add_u32 v11, v11, 2, v4
	ds_read_b32 v11, v11
	v_add_u32_e32 v12, 50, v3
	v_and_b32_e32 v12, 63, v12
	v_lshl_add_u32 v12, v12, 2, v4
	ds_read_b32 v12, v12
	v_add_u32_e32 v13, 51, v3
	v_and_b32_e32 v13, 63, v13
	v_lshl_add_u32 v13, v13, 2, v4
	ds_read_b32 v13, v13
	v_add_u32_e32 v14, 52, v3
	v_and_b32_e32 v14, 63, v14
	v_lshl_add_u32 v14, v14, 2, v4
	ds_read_b32 v14, v14
	v_add_u32_e32 v15, 53, v3
	v_and_b32_e32 v15, 63, v15
	v_lshl_add_u32 v15, v15, 2, v4
	ds_read_b32 v15, v15
	s_waitcnt lgkmcnt(8)
	v_fmac_f32_e32 v5, v6, v6
	s_waitcnt lgkmcnt(7)
	v_fmac_f32_e32 v5, v8, v8
	s_waitcnt lgkmcnt(6)
	v_fmac_f32_e32 v5, v9, v9
	s_waitcnt lgkmcnt(5)
	v_fmac_f32_e32 v5, v10, v10
	s_waitcnt lgkmcnt(4)
	v_fmac_f32_e32 v5, v11, v11
	s_waitcnt lgkmcnt(3)
	v_fmac_f32_e32 v5, v12, v12
	s_waitcnt lgkmcnt(2)
	v_fmac_f32_e32 v5, v13, v13
	s_waitcnt lgkmcnt(1)
	v_fmac_f32_e32 v5, v14, v14
	s_waitcnt lgkmcnt(0)
	v_fmac_f32_e32 v5, v15, v15
	v_add_u32_e32 v6, 54, v3
	v_and_b32_e32 v6, 63, v6
	v_lshl_add_u32 v6, v6, 2, v4
	ds_read_b32 v6, v6
	s_waitcnt lgkmcnt(0)
	v_pk_mul_f32 v[6:7], v[6:7], v[6:7]
	s_nop 0
	v_add_f32_e32 v5, v5, v6
	v_add_f32_e32 v5, v5, v7
	v_add_u32_e32 v6, 56, v3
	v_add_u32_e32 v7, 57, v3
	v_and_b32_e32 v6, 63, v6
	v_and_b32_e32 v7, 63, v7
	v_lshl_add_u32 v6, v6, 2, v4
	v_lshl_add_u32 v7, v7, 2, v4
	ds_read_b32 v6, v6
	ds_read_b32 v7, v7
	s_waitcnt lgkmcnt(0)
	v_pk_mul_f32 v[6:7], v[6:7], v[6:7]
	s_nop 0
	v_add_f32_e32 v5, v5, v6
	v_add_f32_e32 v5, v5, v7
	v_add_u32_e32 v6, 58, v3
	v_add_u32_e32 v7, 59, v3
	v_and_b32_e32 v6, 63, v6
	v_and_b32_e32 v7, 63, v7
	v_lshl_add_u32 v6, v6, 2, v4
	v_lshl_add_u32 v7, v7, 2, v4
	ds_read_b32 v6, v6
	ds_read_b32 v7, v7
	s_waitcnt lgkmcnt(0)
	v_pk_mul_f32 v[6:7], v[6:7], v[6:7]
	s_nop 0
	v_add_f32_e32 v5, v5, v6
	v_add_f32_e32 v5, v5, v7
	v_add_u32_e32 v6, 60, v3
	v_add_u32_e32 v7, 61, v3
	v_and_b32_e32 v6, 63, v6
	v_and_b32_e32 v7, 63, v7
	v_lshl_add_u32 v6, v6, 2, v4
	v_lshl_add_u32 v7, v7, 2, v4
	ds_read_b32 v6, v6
	ds_read_b32 v7, v7
	s_waitcnt lgkmcnt(0)
	v_pk_mul_f32 v[6:7], v[6:7], v[6:7]
	s_nop 0
	v_add_f32_e32 v5, v5, v6
	v_add_f32_e32 v8, v5, v7
	v_add_u32_e32 v5, 62, v3
	v_add_u32_e32 v3, -1, v3
	v_and_b32_e32 v5, 63, v5
	v_and_b32_e32 v3, 63, v3
	v_lshl_add_u32 v5, v5, 2, v4
	v_lshl_add_u32 v3, v3, 2, v4
	ds_read_b32 v6, v5
	ds_read_b32 v7, v3
	s_waitcnt lgkmcnt(0)
	v_pk_mul_f32 v[4:5], v[6:7], v[6:7]
	s_nop 0
	v_add_f32_e32 v3, v8, v4
	v_add_f32_e32 v3, v3, v5
	v_fmamk_f32 v3, v3, 0x3c800000, v231
	v_cmp_gt_f32_e32 vcc, s0, v3
	v_mul_f32_e32 v4, 0x4b800000, v3
	s_mov_b32 s0, 0x3ffffffe
	v_cndmask_b32_e32 v3, v3, v4, vcc
	v_rsq_f32_e32 v3, v3
	v_and_or_b32 v0, v0, s0, v2
	v_lshl_add_u32 v0, v0, 2, v237
	v_mov_b32_e32 v6, v230
	v_mul_f32_e32 v4, 0x45800000, v3
	v_cndmask_b32_e32 v3, v3, v4, vcc
	ds_write_b32 v0, v3
	s_waitcnt lgkmcnt(0)
	s_barrier
	s_lshl_b64 s[0:1], s[70:71], 2
	s_add_u32 s4, s4, s0
	v_lshlrev_b32_e32 v0, 2, v6
	v_and_b32_e32 v0, 60, v0
	v_cndmask_b32_e64 v2, 0, 1, s[6:7]
	s_addc_u32 s5, s3, s1
	v_cmp_ne_u32_e64 s[0:1], 1, v2
	v_lshlrev_b32_e32 v7, 2, v0
	global_load_dwordx4 v[2:5], v7, s[4:5]
	s_branch .LBB0_2090
	v_mov_b32_e32 v4, 1.0
	v_mov_b32_e32 v5, v4
	v_mov_b32_e32 v2, v4
	v_mov_b32_e32 v3, v4
